# static s_setprio 1 for waves 4-7 at each attention item-loop head (on top of v14)
# baseline (speedup 1.0000x reference)
.LBB0_309:
	v_readfirstlane_b32 s98, v147
	s_nop 0
	s_bitcmp1_b32 s98, 8
	s_cbranch_scc0 .Lprio_skip_309
	s_setprio 1

	.amdhsa_kernel _Z4mega6Params
		.amdhsa_group_segment_fixed_size 155664
		.amdhsa_private_segment_fixed_size 0
		.amdhsa_kernarg_size 544
		.amdhsa_user_sgpr_count 2
		.amdhsa_user_sgpr_dispatch_ptr 0
		.amdhsa_user_sgpr_queue_ptr 0
		.amdhsa_user_sgpr_kernarg_segment_ptr 1
		.amdhsa_user_sgpr_dispatch_id 0
		.amdhsa_user_sgpr_kernarg_preload_length 0
		.amdhsa_user_sgpr_kernarg_preload_offset 0
		.amdhsa_user_sgpr_private_segment_size 0
		.amdhsa_uses_dynamic_stack 0
		.amdhsa_enable_private_segment 0
		.amdhsa_system_sgpr_workgroup_id_x 1
		.amdhsa_system_sgpr_workgroup_id_y 0
		.amdhsa_system_sgpr_workgroup_id_z 0
		.amdhsa_system_sgpr_workgroup_info 0
		.amdhsa_system_vgpr_workitem_id 2
		.amdhsa_next_free_vgpr 245
		.amdhsa_next_free_sgpr 102
		.amdhsa_accum_offset 248
		.amdhsa_reserve_vcc 1
		.amdhsa_float_round_mode_32 0
		.amdhsa_float_round_mode_16_64 0
		.amdhsa_float_denorm_mode_32 3
		.amdhsa_float_denorm_mode_16_64 3
		.amdhsa_dx10_clamp 1
		.amdhsa_ieee_mode 1
		.amdhsa_fp16_overflow 0
		.amdhsa_tg_split 0
		.amdhsa_exception_fp_ieee_invalid_op 0
		.amdhsa_exception_fp_denorm_src 0
		.amdhsa_exception_fp_ieee_div_zero 0
		.amdhsa_exception_fp_ieee_overflow 0
		.amdhsa_exception_fp_ieee_underflow 0
		.amdhsa_exception_fp_ieee_inexact 0
		.amdhsa_exception_int_div_zero 0
	.end_amdhsa_kernel

amdhsa.kernels:
  - .agpr_count:     0
    .args:
      - .offset:         0
        .size:           288
        .value_kind:     by_value
      - .offset:         288
        .size:           4
        .value_kind:     hidden_block_count_x
      - .offset:         292
        .size:           4
        .value_kind:     hidden_block_count_y
      - .offset:         296
        .size:           4
        .value_kind:     hidden_block_count_z
      - .offset:         300
        .size:           2
        .value_kind:     hidden_group_size_x
      - .offset:         302
        .size:           2
        .value_kind:     hidden_group_size_y
      - .offset:         304
        .size:           2
        .value_kind:     hidden_group_size_z
      - .offset:         306
        .size:           2
        .value_kind:     hidden_remainder_x
      - .offset:         308
        .size:           2
        .value_kind:     hidden_remainder_y
      - .offset:         310
        .size:           2
        .value_kind:     hidden_remainder_z
      - .offset:         328
        .size:           8
        .value_kind:     hidden_global_offset_x
      - .offset:         336
        .size:           8
        .value_kind:     hidden_global_offset_y
      - .offset:         344
        .size:           8
        .value_kind:     hidden_global_offset_z
      - .offset:         352
        .size:           2
        .value_kind:     hidden_grid_dims
      - .offset:         376
        .size:           8
        .value_kind:     hidden_multigrid_sync_arg
    .group_segment_fixed_size: 155664
    .kernarg_segment_align: 8
    .kernarg_segment_size: 544
    .language:       OpenCL C
    .language_version:
      - 2
      - 0
    .max_flat_workgroup_size: 512
    .name:           _Z4mega6Params
    .private_segment_fixed_size: 0
    .sgpr_count:     108
    .sgpr_spill_count: 290
    .symbol:         _Z4mega6Params.kd
    .uniform_work_group_size: 1
    .uses_dynamic_stack: false
    .vgpr_count:     245
    .vgpr_spill_count: 0
    .wavefront_size: 64
